# S5 mixer: per-wave LDS state image stored with permuted rows so the four lane groups of each 2-byte store hit different banks
# speedup vs baseline: 1.0079x; 1.0076x over previous
.LBB0_855:
	s_or_b64 exec, exec, s[22:23]
	s_waitcnt vmcnt(17)
	v_mul_f32_e32 v4, 0x3fb8aa3b, v114
	v_exp_f32_e32 v136, v4
	s_waitcnt vmcnt(9)
	v_mov_b32_e32 v138, v131
	s_waitcnt vmcnt(2)
	v_pk_add_f32 v[26:27], v[26:27], 0 neg_lo:[1,1] neg_hi:[1,1]
	v_pk_add_f32 v[28:29], v[28:29], 0 neg_lo:[1,1] neg_hi:[1,1]
	v_mul_f32_e32 v4, v136, v130
	v_mul_f32_e32 v4, 0x3fb8aa3b, v4
	v_exp_f32_e32 v13, v4
	v_mul_f32_e32 v4, v136, v131
	v_mul_f32_e32 v4, 0.15915494, v4
	v_cos_f32_e32 v114, v4
	v_sin_f32_e32 v4, v4
	v_pk_add_f32 v[22:23], v[22:23], 0 neg_lo:[1,1] neg_hi:[1,1]
	v_pk_add_f32 v[24:25], v[24:25], 0 neg_lo:[1,1] neg_hi:[1,1]
	v_mul_f32_e32 v159, v13, v114
	v_mul_f32_e32 v115, v13, v4
	v_fma_f32 v114, v13, v114, -1.0
	v_pk_mul_f32 v[4:5], v[130:131], v[130:131]
	v_pk_mul_f32 v[142:143], v[138:139], v[114:115] op_sel:[0,1] op_sel_hi:[0,0]
	v_pk_fma_f32 v[144:145], v[130:131], v[114:115], v[142:143]
	v_pk_fma_f32 v[130:131], v[130:131], v[114:115], v[142:143] op_sel_hi:[0,1,1] neg_lo:[0,0,1] neg_hi:[0,0,1]
	v_pk_add_f32 v[4:5], v[4:5], v[4:5] op_sel:[0,1] op_sel_hi:[0,1]
	v_div_scale_f32 v13, s[22:23], v5, v5, v131
	v_rcp_f32_e32 v114, v13
	v_cvt_pk_bf16_f32 v26, v26, v27
	v_cvt_pk_bf16_f32 v27, v28, v29
	v_mul_f32_e32 v28, v136, v104
	v_fma_f32 v130, -v13, v114, 1.0
	v_fmac_f32_e32 v114, v130, v114
	v_div_scale_f32 v130, vcc, v131, v5, v131
	v_mul_f32_e32 v138, v130, v114
	v_fma_f32 v140, -v13, v138, v130
	v_fmac_f32_e32 v138, v140, v114
	v_fma_f32 v13, -v13, v138, v130
	v_div_fmas_f32 v13, v13, v114, v138
	v_div_fixup_f32 v5, v13, v5, v131
	v_div_scale_f32 v13, s[22:23], v4, v4, v144
	v_rcp_f32_e32 v114, v13
	v_cvt_pk_bf16_f32 v22, v22, v23
	v_cvt_pk_bf16_f32 v23, v24, v25
	s_waitcnt vmcnt(1)
	v_pk_add_f32 v[24:25], v[30:31], 0 neg_lo:[1,1] neg_hi:[1,1]
	v_fma_f32 v130, -v13, v114, 1.0
	v_fmac_f32_e32 v114, v130, v114
	v_div_scale_f32 v130, vcc, v144, v4, v144
	v_mul_f32_e32 v131, v130, v114
	v_fma_f32 v138, -v13, v131, v130
	v_fmac_f32_e32 v131, v138, v114
	v_fma_f32 v13, -v13, v131, v130
	v_div_fmas_f32 v13, v13, v114, v131
	v_div_fixup_f32 v4, v13, v4, v144
	v_pk_mul_f32 v[142:143], v[4:5], v[132:133] op_sel:[0,1] op_sel_hi:[1,0]
	v_pk_mul_f32 v[144:145], v[4:5], v[128:129] op_sel:[0,1] op_sel_hi:[1,0]
	v_pk_mul_f32 v[132:133], v[4:5], v[132:133]
	v_mov_b32_e32 v148, v142
	v_mov_b32_e32 v149, v144
	v_mov_b32_e32 v144, v143
	v_pk_mul_f32 v[128:129], v[4:5], v[128:129]
	v_pk_add_f32 v[142:143], v[148:149], v[144:145] neg_lo:[0,1] neg_hi:[0,1]
	v_mov_b32_e32 v144, v132
	v_mov_b32_e32 v145, v128
	v_mov_b32_e32 v128, v133
	v_pk_add_f32 v[128:129], v[144:145], v[128:129]
	v_pk_mul_f32 v[132:133], v[4:5], v[120:121] op_sel:[0,1] op_sel_hi:[1,0]
	v_pk_mul_f32 v[144:145], v[4:5], v[10:11] op_sel:[0,1] op_sel_hi:[1,0]
	v_pk_mul_f32 v[120:121], v[4:5], v[120:121]
	v_mov_b32_e32 v148, v132
	v_mov_b32_e32 v149, v144
	v_mov_b32_e32 v144, v133
	v_pk_mul_f32 v[10:11], v[4:5], v[10:11]
	v_pk_add_f32 v[132:133], v[148:149], v[144:145] neg_lo:[0,1] neg_hi:[0,1]
	v_mov_b32_e32 v144, v120
	v_mov_b32_e32 v145, v10
	v_mov_b32_e32 v10, v121
	v_pk_add_f32 v[30:31], v[32:33], 0 neg_lo:[1,1] neg_hi:[1,1]
	v_mul_f32_e32 v28, 0x3fb8aa3b, v28
	v_pk_add_f32 v[10:11], v[144:145], v[10:11]
	v_pk_mul_f32 v[120:121], v[4:5], v[8:9] op_sel:[0,1] op_sel_hi:[1,0]
	v_pk_mul_f32 v[144:145], v[4:5], v[6:7] op_sel:[0,1] op_sel_hi:[1,0]
	v_cvt_pk_bf16_f32 v24, v24, v25
	v_cvt_pk_bf16_f32 v25, v30, v31
	v_exp_f32_e32 v30, v28
	v_mul_f32_e32 v28, v136, v105
	v_pk_mul_f32 v[8:9], v[4:5], v[8:9]
	v_mov_b32_e32 v148, v120
	v_mov_b32_e32 v149, v144
	v_mov_b32_e32 v144, v121
	v_pk_mul_f32 v[6:7], v[4:5], v[6:7]
	v_mul_f32_e32 v28, 0.15915494, v28
	v_pk_add_f32 v[120:121], v[148:149], v[144:145] neg_lo:[0,1] neg_hi:[0,1]
	v_mov_b32_e32 v144, v8
	v_mov_b32_e32 v145, v6
	v_mov_b32_e32 v6, v9
	v_cos_f32_e32 v31, v28
	v_sin_f32_e32 v28, v28
	v_pk_mul_f32 v[130:131], v[4:5], v[134:135] op_sel:[0,1] op_sel_hi:[1,0]
	v_pk_add_f32 v[8:9], v[144:145], v[6:7]
	v_pk_mul_f32 v[6:7], v[4:5], v[126:127] op_sel:[0,1] op_sel_hi:[1,0]
	v_pk_mul_f32 v[134:135], v[4:5], v[134:135]
	v_mov_b32_e32 v144, v130
	v_mov_b32_e32 v145, v6
	v_mov_b32_e32 v6, v131
	v_pk_mul_f32 v[4:5], v[4:5], v[126:127]
	v_pk_add_f32 v[130:131], v[144:145], v[6:7] neg_lo:[0,1] neg_hi:[0,1]
	v_mov_b32_e32 v6, v134
	v_mov_b32_e32 v7, v4
	v_mov_b32_e32 v4, v135
	v_pk_add_f32 v[126:127], v[6:7], v[4:5]
	v_cvt_pk_bf16_f32 v4, v120, v121
	v_mul_f32_e32 v114, v30, v31
	v_mul_f32_e32 v121, v30, v28
	v_fma_f32 v120, v30, v31, -1.0
	v_mov_b32_e32 v30, v105
	v_pk_mul_f32 v[28:29], v[104:105], v[104:105]
	v_pk_mul_f32 v[30:31], v[30:31], v[120:121] op_sel:[0,1] op_sel_hi:[0,0]
	v_pk_fma_f32 v[32:33], v[104:105], v[120:121], v[30:31]
	v_pk_fma_f32 v[30:31], v[104:105], v[120:121], v[30:31] op_sel_hi:[0,1,1] neg_lo:[0,0,1] neg_hi:[0,0,1]
	v_pk_add_f32 v[28:29], v[28:29], v[28:29] op_sel:[0,1] op_sel_hi:[0,1]
	v_div_scale_f32 v30, s[22:23], v29, v29, v31
	v_rcp_f32_e32 v33, v30
	v_cvt_pk_bf16_f32 v18, v18, v19
	v_cvt_pk_bf16_f32 v19, v20, v21
	v_pk_add_f32 v[20:21], v[34:35], 0 neg_lo:[1,1] neg_hi:[1,1]
	v_pk_add_f32 v[34:35], v[36:37], 0 neg_lo:[1,1] neg_hi:[1,1]
	v_cvt_pk_bf16_f32 v20, v20, v21
	v_cvt_pk_bf16_f32 v21, v34, v35
	v_fma_f32 v34, -v30, v33, 1.0
	v_fmac_f32_e32 v33, v34, v33
	v_div_scale_f32 v34, vcc, v31, v29, v31
	v_mul_f32_e32 v35, v34, v33
	v_fma_f32 v36, -v30, v35, v34
	v_fmac_f32_e32 v35, v36, v33
	v_fma_f32 v30, -v30, v35, v34
	v_div_fmas_f32 v30, v30, v33, v35
	v_div_fixup_f32 v29, v30, v29, v31
	v_div_scale_f32 v30, s[22:23], v28, v28, v32
	v_rcp_f32_e32 v31, v30
	v_cvt_pk_bf16_f32 v14, v14, v15
	v_cvt_pk_bf16_f32 v15, v16, v17
	v_cvt_pk_bf16_f32 v16, v38, v39
	v_fma_f32 v33, -v30, v31, 1.0
	v_fmac_f32_e32 v31, v33, v31
	v_div_scale_f32 v33, vcc, v32, v28, v32
	v_mul_f32_e32 v34, v33, v31
	v_fma_f32 v35, -v30, v34, v33
	v_fmac_f32_e32 v34, v35, v31
	v_fma_f32 v30, -v30, v34, v33
	v_div_fmas_f32 v30, v30, v31, v34
	v_div_fixup_f32 v28, v30, v28, v32
	v_pk_mul_f32 v[34:35], v[28:29], v[106:107] op_sel:[0,1] op_sel_hi:[1,0]
	v_pk_mul_f32 v[38:39], v[28:29], v[102:103] op_sel:[0,1] op_sel_hi:[1,0]
	v_cvt_pk_bf16_f32 v17, v40, v41
	v_mov_b32_e32 v40, v34
	v_mov_b32_e32 v41, v38
	v_mov_b32_e32 v38, v35
	v_pk_mul_f32 v[36:37], v[28:29], v[106:107]
	v_pk_add_f32 v[34:35], v[40:41], v[38:39] neg_lo:[0,1] neg_hi:[0,1]
	v_pk_mul_f32 v[38:39], v[28:29], v[102:103]
	v_mov_b32_e32 v40, v36
	v_mov_b32_e32 v41, v38
	v_mov_b32_e32 v38, v37
	v_cvt_pk_bf16_f32 v8, v8, v9
	v_cvt_pk_bf16_f32 v9, v10, v11
	v_cvt_pk_bf16_f32 v11, v126, v127
	v_or_b32_e32 v127, 2, v12
	v_cvt_pk_bf16_f32 v12, v52, v53
	v_pk_add_f32 v[36:37], v[40:41], v[38:39]
	v_pk_mul_f32 v[38:39], v[28:29], v[98:99] op_sel:[0,1] op_sel_hi:[1,0]
	v_pk_mul_f32 v[52:53], v[28:29], v[96:97] op_sel:[0,1] op_sel_hi:[1,0]
	v_cvt_pk_bf16_f32 v13, v54, v55
	v_mov_b32_e32 v54, v38
	v_mov_b32_e32 v55, v52
	v_mov_b32_e32 v52, v39
	v_pk_mul_f32 v[40:41], v[28:29], v[98:99]
	v_pk_add_f32 v[38:39], v[54:55], v[52:53] neg_lo:[0,1] neg_hi:[0,1]
	v_pk_mul_f32 v[52:53], v[28:29], v[96:97]
	v_mov_b32_e32 v54, v40
	v_mov_b32_e32 v55, v52
	v_mov_b32_e32 v52, v41
	v_pk_add_f32 v[40:41], v[54:55], v[52:53]
	v_pk_mul_f32 v[52:53], v[28:29], v[94:95] op_sel:[0,1] op_sel_hi:[1,0]
	v_pk_mul_f32 v[54:55], v[28:29], v[94:95]
	v_pk_mul_f32 v[94:95], v[28:29], v[92:93] op_sel:[0,1] op_sel_hi:[1,0]
	v_mov_b32_e32 v96, v52
	v_mov_b32_e32 v97, v94
	v_mov_b32_e32 v94, v53
	v_pk_mul_f32 v[92:93], v[28:29], v[92:93]
	v_pk_add_f32 v[52:53], v[96:97], v[94:95] neg_lo:[0,1] neg_hi:[0,1]
	v_mov_b32_e32 v94, v54
	v_mov_b32_e32 v95, v92
	v_mov_b32_e32 v92, v55
	v_pk_mul_f32 v[30:31], v[28:29], v[124:125] op_sel:[0,1] op_sel_hi:[1,0]
	v_pk_mul_f32 v[32:33], v[28:29], v[124:125]
	v_pk_add_f32 v[54:55], v[94:95], v[92:93]
	v_pk_mul_f32 v[92:93], v[28:29], v[100:101] op_sel:[0,1] op_sel_hi:[1,0]
	v_pk_mul_f32 v[28:29], v[28:29], v[100:101]
	v_mov_b32_e32 v94, v30
	v_mov_b32_e32 v95, v92
	v_mov_b32_e32 v92, v31
	v_mov_b32_e32 v30, v32
	v_mov_b32_e32 v31, v28
	v_mov_b32_e32 v28, v33
	v_pk_add_f32 v[92:93], v[94:95], v[92:93] neg_lo:[0,1] neg_hi:[0,1]
	v_pk_add_f32 v[94:95], v[30:31], v[28:29]
	v_cvt_pk_bf16_f32 v30, v34, v35
	v_cvt_pk_bf16_f32 v34, v36, v37
	v_add_f32_e32 v37, v159, v159
	v_mul_f32_e32 v36, v115, v115
	v_mul_f32_e32 v37, v115, v37
	v_cvt_pk_bf16_f32 v29, v38, v39
	v_fma_f32 v36, v159, v159, -v36
	v_mul_f32_e32 v38, v37, v37
	v_fma_f32 v38, v36, v36, -v38
	v_add_f32_e32 v36, v36, v36
	v_mul_f32_e32 v36, v37, v36
	v_mul_f32_e32 v37, v36, v36
	v_fma_f32 v124, v38, v38, -v37
	v_add_f32_e32 v37, v38, v38
	v_mul_f32_e32 v126, v36, v37
	v_mul_f32_e32 v36, v136, v84
	v_mul_f32_e32 v36, 0x3fb8aa3b, v36
	v_exp_f32_e32 v38, v36
	v_mul_f32_e32 v36, v136, v85
	v_mul_f32_e32 v36, 0.15915494, v36
	v_cos_f32_e32 v39, v36
	v_sin_f32_e32 v36, v36
	v_cvt_pk_bf16_f32 v10, v128, v129
	v_cvt_pk_bf16_f32 v33, v40, v41
	v_mul_f32_e32 v120, v38, v39
	v_mul_f32_e32 v129, v38, v36
	v_fma_f32 v128, v38, v39, -1.0
	v_mov_b32_e32 v38, v85
	v_pk_mul_f32 v[36:37], v[84:85], v[84:85]
	v_pk_mul_f32 v[38:39], v[38:39], v[128:129] op_sel:[0,1] op_sel_hi:[0,0]
	v_pk_fma_f32 v[40:41], v[84:85], v[128:129], v[38:39]
	v_pk_fma_f32 v[38:39], v[84:85], v[128:129], v[38:39] op_sel_hi:[0,1,1] neg_lo:[0,0,1] neg_hi:[0,0,1]
	v_pk_add_f32 v[36:37], v[36:37], v[36:37] op_sel:[0,1] op_sel_hi:[0,1]
	v_div_scale_f32 v38, s[22:23], v37, v37, v39
	v_rcp_f32_e32 v41, v38
	v_cvt_pk_bf16_f32 v28, v52, v53
	v_cvt_pk_bf16_f32 v32, v54, v55
	v_cvt_pk_bf16_f32 v7, v130, v131
	v_fma_f32 v52, -v38, v41, 1.0
	v_fmac_f32_e32 v41, v52, v41
	v_div_scale_f32 v52, vcc, v39, v37, v39
	v_mul_f32_e32 v53, v52, v41
	v_fma_f32 v54, -v38, v53, v52
	v_fmac_f32_e32 v53, v54, v41
	v_fma_f32 v38, -v38, v53, v52
	v_div_fmas_f32 v38, v38, v41, v53
	v_div_fixup_f32 v37, v38, v37, v39
	v_div_scale_f32 v38, s[22:23], v36, v36, v40
	v_rcp_f32_e32 v39, v38
	v_cvt_pk_bf16_f32 v5, v132, v133
	v_lshlrev_b32_e32 v141, 2, v158
	v_cvt_pk_bf16_f32 v6, v142, v143
	v_fma_f32 v41, -v38, v39, 1.0
	v_fmac_f32_e32 v39, v41, v39
	v_div_scale_f32 v41, vcc, v40, v36, v40
	v_mul_f32_e32 v52, v41, v39
	v_fma_f32 v53, -v38, v52, v41
	v_fmac_f32_e32 v52, v53, v39
	v_fma_f32 v38, -v38, v52, v41
	v_div_fmas_f32 v38, v38, v39, v52
	v_div_fixup_f32 v36, v38, v36, v40
	v_pk_mul_f32 v[52:53], v[36:37], v[86:87] op_sel:[0,1] op_sel_hi:[1,0]
	v_pk_mul_f32 v[84:85], v[36:37], v[82:83] op_sel:[0,1] op_sel_hi:[1,0]
	v_pk_mul_f32 v[54:55], v[36:37], v[86:87]
	v_mov_b32_e32 v86, v52
	v_mov_b32_e32 v87, v84
	v_mov_b32_e32 v84, v53
	v_pk_mul_f32 v[82:83], v[36:37], v[82:83]
	v_pk_add_f32 v[52:53], v[86:87], v[84:85] neg_lo:[0,1] neg_hi:[0,1]
	v_mov_b32_e32 v84, v54
	v_mov_b32_e32 v85, v82
	v_mov_b32_e32 v82, v55
	v_pk_add_f32 v[54:55], v[84:85], v[82:83]
	v_pk_mul_f32 v[82:83], v[36:37], v[78:79] op_sel:[0,1] op_sel_hi:[1,0]
	v_pk_mul_f32 v[84:85], v[36:37], v[76:77] op_sel:[0,1] op_sel_hi:[1,0]
	v_pk_mul_f32 v[78:79], v[36:37], v[78:79]
	v_mov_b32_e32 v86, v82
	v_mov_b32_e32 v87, v84
	v_mov_b32_e32 v84, v83
	v_pk_mul_f32 v[76:77], v[36:37], v[76:77]
	v_pk_add_f32 v[82:83], v[86:87], v[84:85] neg_lo:[0,1] neg_hi:[0,1]
	v_mov_b32_e32 v84, v78
	v_mov_b32_e32 v85, v76
	v_mov_b32_e32 v76, v79
	v_pk_add_f32 v[76:77], v[84:85], v[76:77]
	v_pk_mul_f32 v[78:79], v[36:37], v[74:75] op_sel:[0,1] op_sel_hi:[1,0]
	v_pk_mul_f32 v[84:85], v[36:37], v[42:43] op_sel:[0,1] op_sel_hi:[1,0]
	v_pk_mul_f32 v[74:75], v[36:37], v[74:75]
	v_mov_b32_e32 v86, v78
	v_mov_b32_e32 v87, v84
	v_mov_b32_e32 v84, v79
	v_pk_mul_f32 v[42:43], v[36:37], v[42:43]
	v_pk_mul_f32 v[38:39], v[36:37], v[88:89] op_sel:[0,1] op_sel_hi:[1,0]
	v_pk_mul_f32 v[40:41], v[36:37], v[88:89]
	v_pk_add_f32 v[78:79], v[86:87], v[84:85] neg_lo:[0,1] neg_hi:[0,1]
	v_mov_b32_e32 v84, v74
	v_mov_b32_e32 v85, v42
	v_mov_b32_e32 v42, v75
	v_pk_mul_f32 v[74:75], v[36:37], v[80:81] op_sel:[0,1] op_sel_hi:[1,0]
	v_pk_mul_f32 v[36:37], v[36:37], v[80:81]
	v_pk_add_f32 v[42:43], v[84:85], v[42:43]
	v_mov_b32_e32 v84, v38
	v_mov_b32_e32 v85, v74
	v_mov_b32_e32 v74, v39
	v_mov_b32_e32 v38, v40
	v_mov_b32_e32 v39, v36
	v_mov_b32_e32 v36, v41
	v_pk_add_f32 v[80:81], v[38:39], v[36:37]
	v_cvt_pk_bf16_f32 v38, v52, v53
	v_add_f32_e32 v53, v114, v114
	v_mul_f32_e32 v52, v121, v121
	v_mul_f32_e32 v53, v121, v53
	v_cvt_pk_bf16_f32 v40, v42, v43
	v_cvt_pk_bf16_f32 v42, v54, v55
	v_fma_f32 v52, v114, v114, -v52
	v_mul_f32_e32 v54, v53, v53
	v_fma_f32 v54, v52, v52, -v54
	v_add_f32_e32 v52, v52, v52
	v_mul_f32_e32 v52, v53, v52
	v_mul_f32_e32 v53, v52, v52
	v_fma_f32 v130, v54, v54, -v53
	v_add_f32_e32 v53, v54, v54
	v_mul_f32_e32 v132, v52, v53
	v_mul_f32_e32 v52, v68, v136
	v_mul_f32_e32 v52, 0x3fb8aa3b, v52
	v_exp_f32_e32 v54, v52
	v_mul_f32_e32 v52, v136, v69
	v_mul_f32_e32 v52, 0.15915494, v52
	v_cos_f32_e32 v55, v52
	v_sin_f32_e32 v52, v52
	v_pk_add_f32 v[74:75], v[84:85], v[74:75] neg_lo:[0,1] neg_hi:[0,1]
	v_cvt_pk_bf16_f32 v41, v76, v77
	v_mul_f32_e32 v128, v54, v55
	v_mul_f32_e32 v135, v54, v52
	v_fma_f32 v134, v54, v55, -1.0
	v_mov_b32_e32 v54, v69
	v_pk_mul_f32 v[52:53], v[68:69], v[68:69]
	v_pk_mul_f32 v[54:55], v[54:55], v[134:135] op_sel:[0,1] op_sel_hi:[0,0]
	v_cvt_pk_bf16_f32 v39, v74, v75
	v_pk_fma_f32 v[74:75], v[68:69], v[134:135], v[54:55]
	v_pk_fma_f32 v[54:55], v[68:69], v[134:135], v[54:55] op_sel_hi:[0,1,1] neg_lo:[0,0,1] neg_hi:[0,0,1]
	v_pk_add_f32 v[52:53], v[52:53], v[52:53] op_sel:[0,1] op_sel_hi:[0,1]
	v_div_scale_f32 v54, s[22:23], v53, v53, v55
	v_rcp_f32_e32 v68, v54
	v_mul_f32_e32 v134, 0, v135
	v_mul_f32_e32 v169, 0, v129
	v_mul_f32_e32 v171, 0, v121
	v_fma_f32 v69, -v54, v68, 1.0
	v_fmac_f32_e32 v68, v69, v68
	v_div_scale_f32 v69, vcc, v55, v53, v55
	v_mul_f32_e32 v75, v69, v68
	v_fma_f32 v76, -v54, v75, v69
	v_fmac_f32_e32 v75, v76, v68
	v_fma_f32 v54, -v54, v75, v69
	v_div_fmas_f32 v54, v54, v68, v75
	v_div_fixup_f32 v53, v54, v53, v55
	v_div_scale_f32 v54, s[22:23], v52, v52, v74
	v_rcp_f32_e32 v55, v54
	s_movk_i32 s22, 0x2200
	v_mul_f32_e32 v173, 0, v115
	v_cvt_pk_bf16_f32 v31, v92, v93
	v_fma_f32 v68, -v54, v55, 1.0
	v_fmac_f32_e32 v55, v68, v55
	v_div_scale_f32 v68, vcc, v74, v52, v74
	v_mul_f32_e32 v69, v68, v55
	v_fma_f32 v75, -v54, v69, v68
	v_fmac_f32_e32 v69, v75, v55
	v_fma_f32 v54, -v54, v69, v68
	v_div_fmas_f32 v54, v54, v55, v69
	v_div_fixup_f32 v52, v54, v52, v74
	v_pk_mul_f32 v[54:55], v[52:53], v[72:73] op_sel:[0,1] op_sel_hi:[1,0]
	v_pk_mul_f32 v[68:69], v[52:53], v[72:73]
	v_pk_mul_f32 v[72:73], v[52:53], v[70:71] op_sel:[0,1] op_sel_hi:[1,0]
	v_pk_mul_f32 v[74:75], v[52:53], v[66:67] op_sel:[0,1] op_sel_hi:[1,0]
	v_pk_mul_f32 v[70:71], v[52:53], v[70:71]
	v_mov_b32_e32 v76, v72
	v_mov_b32_e32 v77, v74
	v_mov_b32_e32 v74, v73
	v_pk_mul_f32 v[66:67], v[52:53], v[66:67]
	v_pk_add_f32 v[72:73], v[76:77], v[74:75] neg_lo:[0,1] neg_hi:[0,1]
	v_mov_b32_e32 v74, v70
	v_mov_b32_e32 v75, v66
	v_mov_b32_e32 v66, v71
	v_pk_add_f32 v[66:67], v[74:75], v[66:67]
	v_pk_mul_f32 v[70:71], v[52:53], v[62:63] op_sel:[0,1] op_sel_hi:[1,0]
	v_pk_mul_f32 v[74:75], v[52:53], v[60:61] op_sel:[0,1] op_sel_hi:[1,0]
	v_pk_mul_f32 v[62:63], v[52:53], v[62:63]
	v_mov_b32_e32 v76, v70
	v_mov_b32_e32 v77, v74
	v_mov_b32_e32 v74, v71
	v_pk_mul_f32 v[60:61], v[52:53], v[60:61]
	v_pk_add_f32 v[70:71], v[76:77], v[74:75] neg_lo:[0,1] neg_hi:[0,1]
	v_mov_b32_e32 v74, v62
	v_mov_b32_e32 v75, v60
	v_mov_b32_e32 v60, v63
	v_pk_add_f32 v[60:61], v[74:75], v[60:61]
	v_pk_mul_f32 v[62:63], v[52:53], v[58:59] op_sel:[0,1] op_sel_hi:[1,0]
	v_pk_mul_f32 v[74:75], v[52:53], v[56:57] op_sel:[0,1] op_sel_hi:[1,0]
	v_pk_mul_f32 v[58:59], v[52:53], v[58:59]
	v_mov_b32_e32 v76, v62
	v_mov_b32_e32 v77, v74
	v_mov_b32_e32 v74, v63
	v_pk_mul_f32 v[56:57], v[52:53], v[56:57]
	v_pk_add_f32 v[62:63], v[76:77], v[74:75] neg_lo:[0,1] neg_hi:[0,1]
	v_mov_b32_e32 v74, v58
	v_mov_b32_e32 v75, v56
	v_mov_b32_e32 v56, v59
	v_pk_add_f32 v[56:57], v[74:75], v[56:57]
	v_pk_mul_f32 v[58:59], v[52:53], v[64:65] op_sel:[0,1] op_sel_hi:[1,0]
	v_pk_mul_f32 v[52:53], v[52:53], v[64:65]
	v_cvt_pk_bf16_f32 v56, v56, v57
	v_cvt_pk_bf16_f32 v57, v60, v61
	v_add_f32_e32 v61, v120, v120
	v_mov_b32_e32 v74, v54
	v_mov_b32_e32 v75, v58
	v_mov_b32_e32 v58, v55
	v_mov_b32_e32 v54, v68
	v_mov_b32_e32 v55, v52
	v_mov_b32_e32 v52, v69
	v_mul_f32_e32 v60, v129, v129
	v_mul_f32_e32 v61, v129, v61
	v_pk_add_f32 v[64:65], v[54:55], v[52:53]
	v_cvt_pk_bf16_f32 v52, v62, v63
	v_fma_f32 v60, v120, v120, -v60
	v_mul_f32_e32 v62, v61, v61
	v_fma_f32 v62, v60, v60, -v62
	v_add_f32_e32 v60, v60, v60
	v_mul_f32_e32 v60, v61, v60
	v_mul_f32_e32 v61, v60, v60
	v_fma_f32 v136, v62, v62, -v61
	v_add_f32_e32 v61, v62, v62
	v_add_f32_e32 v62, v128, v128
	v_mul_f32_e32 v138, v60, v61
	v_mul_f32_e32 v61, v135, v135
	v_mul_f32_e32 v62, v135, v62
	v_fma_f32 v61, v128, v128, -v61
	v_mul_f32_e32 v63, v62, v62
	v_fma_f32 v63, v61, v61, -v63
	v_add_f32_e32 v61, v61, v61
	v_mul_f32_e32 v61, v62, v61
	v_mul_f32_e32 v62, v61, v61
	v_mul_lo_u32 v60, v137, s22
	v_fma_f32 v140, v63, v63, -v62
	v_add_f32_e32 v62, v63, v63
	v_mul_f32_e32 v142, v61, v62
	v_add_u32_e32 v62, 0, v60
	v_lshlrev_b32_e32 v60, 1, v141
	v_mov_b32_e32 v61, v177
	v_lshl_add_u64 v[144:145], v[90:91], 0, v[60:61]
	v_and_or_b32 v60, v229, 64, v176
	v_lshlrev_b32_e32 v161, 2, v60
	v_mul_u32_u24_e32 v60, 0x110, v158
	v_add3_u32 v165, v62, v60, v139
	v_mul_u32_u24_e32 v60, 0x110, v127
	v_pk_add_f32 v[58:59], v[74:75], v[58:59] neg_lo:[0,1] neg_hi:[0,1]
	v_lshl_add_u32 v61, v158, 4, v62
	v_add_u32_e32 v166, 0x880, v165
	v_lshrrev_b32_e32 v60, 3, v176
	v_and_b32_e32 v190, 7, v176
	v_lshl_or_b32 v60, v190, 2, v60
	v_mul_u32_u24_e32 v60, 0x110, v60
	v_cvt_pk_bf16_f32 v55, v58, v59
	v_cvt_pk_bf16_f32 v58, v66, v67
	v_cvt_pk_bf16_f32 v59, v64, v65
	s_and_b64 s[22:23], exec, s[2:3]
	v_add_u32_e32 v190, v61, v60
	s_waitcnt vmcnt(0)
	v_mov_b64_e32 v[66:67], v[46:47]
	v_mov_b64_e32 v[62:63], v[50:51]
	v_cvt_pk_bf16_f32 v35, v94, v95
	v_cvt_pk_bf16_f32 v36, v78, v79
	v_cvt_pk_bf16_f32 v37, v82, v83
	v_cvt_pk_bf16_f32 v43, v80, v81
	v_cvt_pk_bf16_f32 v53, v70, v71
	v_cvt_pk_bf16_f32 v54, v72, v73
	s_cselect_b32 s46, 64, 2
	s_mov_b32 s47, 0
	v_fma_f32 v160, v128, 0, -v134
	v_fmac_f32_e32 v134, 0, v128
	v_cmp_eq_u32_e32 vcc, 1, v158
	v_or_b32_e32 v162, 64, v161
	v_cmp_eq_u32_e64 s[42:43], 2, v158
	v_or_b32_e32 v163, 0x80, v161
	v_cmp_eq_u32_e64 s[44:45], 3, v158
	v_or_b32_e32 v164, 0xc0, v161
	v_add_u32_e32 v167, 0x1100, v165
	v_add_u32_e32 v168, 0x1980, v165
	v_fma_f32 v170, v120, 0, -v169
	v_fmac_f32_e32 v169, 0, v120
	v_fma_f32 v172, v114, 0, -v171
	v_fmac_f32_e32 v171, 0, v114
	v_fma_f32 v174, v159, 0, -v173
	v_fmac_f32_e32 v173, 0, v159
	v_mov_b32_e32 v125, v124
	v_mov_b32_e32 v127, v126
	v_mov_b32_e32 v131, v130
	v_mov_b32_e32 v133, v132
	v_mov_b32_e32 v137, v136
	v_mov_b32_e32 v139, v138
	v_mov_b32_e32 v141, v140
	v_mov_b32_e32 v143, v142
	v_add_u32_e32 v175, v146, v147
	v_mov_b64_e32 v[64:65], v[44:45]
	v_mov_b64_e32 v[60:61], v[48:49]
	s_add_i32 s47, s47, 1
	s_cmp_ge_u32 s47, s46
	s_cbranch_scc1 .LBB0_862
	s_branch .LBB0_857

.LBB0_862:
	v_add_u32_e32 v68, s29, v176
	v_ashrrev_i32_e32 v69, 31, v68
	v_mfma_f32_16x16x32_bf16 v[192:195], v[48:51], v[56:59], 0
	v_lshlrev_b64 v[70:71], 10, v[68:69]
	v_add_u32_e32 v68, 16, v68
	v_ashrrev_i32_e32 v69, 31, v68
	v_mfma_f32_16x16x32_bf16 v[154:157], v[48:51], v[52:55], 0
	v_lshlrev_b64 v[68:69], 10, v[68:69]
	v_lshl_add_u64 v[146:147], v[144:145], 0, v[68:69]
	s_nop 1
	v_add_f32_e32 v69, v134, v192
	v_lshl_add_u64 v[148:149], v[144:145], 0, v[70:71]
	v_mul_f32_e32 v70, v135, v69
	s_nop 0
	v_add_f32_e32 v68, v160, v154
	v_mul_f32_e32 v69, v128, v69
	v_fmac_f32_e32 v69, v135, v68
	v_fma_f32 v70, v128, v68, -v70
	v_add_f32_e32 v73, v193, v69
	v_add_f32_e32 v72, v155, v70
	v_mul_f32_e32 v68, v135, v73
	v_fma_f32 v74, v128, v72, -v68
	v_mul_f32_e32 v77, v135, v72
	v_add_f32_e32 v76, v156, v74
	v_fmac_f32_e32 v77, v128, v73
	v_mfma_f32_16x16x32_bf16 v[92:95], v[48:51], v[36:39], 0
	v_mul_f32_e32 v206, v142, v110
	v_fma_f32 v207, v140, v111, -v206
	v_mul_f32_e32 v206, v142, v111
	v_mfma_f32_16x16x32_bf16 v[104:107], v[48:51], v[40:43], 0
	v_fmac_f32_e32 v206, v140, v110
	global_load_dwordx2 v[152:153], v[148:149], off
	global_load_dwordx2 v[150:151], v[146:147], off
	s_add_i32 s29, s29, 32
	v_mfma_f32_16x16x32_bf16 v[84:87], v[48:51], v[28:31], 0
	s_cmp_eq_u32 s46, s47
	v_mfma_f32_16x16x32_bf16 v[88:91], v[48:51], v[32:35], 0
	v_mfma_f32_16x16x32_bf16 v[68:71], v[48:51], v[4:7], 0
	v_mfma_f32_16x16x32_bf16 v[72:75], v[48:51], v[8:11], 0
	v_add_f32_e32 v48, v194, v77
	v_mul_f32_e32 v50, v135, v76
	v_mul_f32_e32 v49, v135, v48
	v_fmac_f32_e32 v50, v128, v48
	v_fma_f32 v49, v128, v76, -v49
	v_mfma_f32_16x16x32_bf16 v[200:203], v[44:47], v[56:59], 0
	v_add_f32_e32 v48, v195, v50
	v_add_f32_e32 v49, v157, v49
	v_mul_f32_e32 v50, v135, v48
	v_mfma_f32_16x16x32_bf16 v[196:199], v[44:47], v[52:55], 0
	v_fma_f32 v50, v128, v49, -v50
	v_mul_f32_e32 v49, v135, v49
	v_fmac_f32_e32 v49, v128, v48
	s_nop 0
	v_add_f32_e32 v48, v200, v49
	v_mul_f32_e32 v49, v135, v48
	s_nop 1
	v_add_f32_e32 v50, v196, v50
	v_fma_f32 v49, v128, v50, -v49
	v_add_f32_e32 v191, v197, v49
	v_mul_f32_e32 v49, v135, v50
	v_fmac_f32_e32 v49, v128, v48
	v_add_f32_e32 v204, v201, v49
	v_mul_f32_e32 v48, v135, v204
	v_fma_f32 v205, v128, v191, -v48
	v_mul_f32_e32 v191, v135, v191
	v_fmac_f32_e32 v191, v128, v204
	v_add_f32_e32 v191, v202, v191
	v_add_f32_e32 v205, v198, v205
	v_mul_f32_e32 v204, v135, v191
	v_fma_f32 v204, v128, v205, -v204
	v_add_f32_e32 v212, v199, v204
	v_mul_f32_e32 v204, v135, v205
	v_fmac_f32_e32 v204, v128, v191
	v_add_f32_e32 v191, v203, v204
	ds_bpermute_b32 v205, v161, v212
	ds_bpermute_b32 v204, v161, v191
	ds_bpermute_b32 v209, v162, v212
	ds_bpermute_b32 v208, v162, v191
	ds_bpermute_b32 v211, v163, v212
	ds_bpermute_b32 v210, v163, v191
	s_waitcnt lgkmcnt(4)
	v_pk_add_f32 v[204:205], v[206:207], v[204:205]
	ds_bpermute_b32 v213, v164, v212
	ds_bpermute_b32 v212, v164, v191
	v_cndmask_b32_e32 v191, v111, v205, vcc
	v_cndmask_b32_e32 v214, v110, v204, vcc
	v_pk_mul_f32 v[110:111], v[142:143], v[204:205]
	v_mfma_f32_16x16x32_bf16 v[100:103], v[44:47], v[40:43], 0
	v_fma_f32 v206, v140, v204, v111
	v_fma_f32 v207, v141, v205, v110
	v_pk_fma_f32 v[110:111], v[140:141], v[204:205], v[110:111] op_sel:[0,0,1] op_sel_hi:[1,1,0] neg_lo:[0,0,1] neg_hi:[0,0,1]
	s_nop 0
	v_mov_b32_e32 v207, v111
	s_waitcnt lgkmcnt(4)
	v_pk_add_f32 v[110:111], v[206:207], v[208:209]
	v_mfma_f32_16x16x32_bf16 v[96:99], v[44:47], v[36:39], 0
	v_mul_f32_e64 v204, v142, v110
	v_mul_f32_e64 v205, v143, v111
	v_cndmask_b32_e64 v191, v191, v111, s[42:43]
	v_cndmask_b32_e64 v208, v214, v110, s[42:43]
	v_pk_fma_f32 v[206:207], v[140:141], v[110:111], v[204:205] op_sel:[0,0,1] op_sel_hi:[1,1,0]
	v_pk_fma_f32 v[110:111], v[140:141], v[110:111], v[204:205] op_sel:[0,0,1] op_sel_hi:[1,1,0] neg_lo:[0,0,1] neg_hi:[0,0,1]
	v_mfma_f32_16x16x32_bf16 v[80:83], v[44:47], v[32:35], 0
	v_mov_b32_e32 v207, v111
	s_waitcnt lgkmcnt(2)
	v_pk_add_f32 v[110:111], v[206:207], v[210:211]
	s_nop 0
	v_cndmask_b32_e64 v208, v208, v110, s[44:45]
	v_pk_mul_f32 v[204:205], v[142:143], v[110:111]
	v_cndmask_b32_e64 v191, v191, v111, s[44:45]
	v_pk_fma_f32 v[206:207], v[140:141], v[110:111], v[204:205] op_sel:[0,0,1] op_sel_hi:[1,1,0]
	v_pk_fma_f32 v[110:111], v[140:141], v[110:111], v[204:205] op_sel:[0,0,1] op_sel_hi:[1,1,0] neg_lo:[0,0,1] neg_hi:[0,0,1]
	v_mul_f32_e32 v204, v135, v208
	v_fma_f32 v204, v128, v191, -v204
	v_mul_f32_e32 v191, v135, v191
	v_add_f32_e32 v154, v154, v204
	v_fmac_f32_e32 v191, v128, v208
	v_add_f32_e32 v191, v192, v191
	v_cvt_pk_bf16_f32 v192, v154, s0
	ds_write_b16 v165, v192
	v_cvt_pk_bf16_f32 v192, v191, s0
	ds_write_b16 v165, v192 offset:128
	v_mul_f32_e32 v192, v135, v191
	v_fma_f32 v192, v128, v154, -v192
	v_mul_f32_e32 v154, v135, v154
	v_add_f32_e32 v155, v155, v192
	v_fmac_f32_e32 v154, v128, v191
	v_add_f32_e32 v154, v193, v154
	v_cvt_pk_bf16_f32 v191, v155, s0
	ds_write_b16 v165, v191 offset:1088
	v_cvt_pk_bf16_f32 v191, v154, s0
	ds_write_b16 v165, v191 offset:1216
	v_mul_f32_e32 v191, v135, v154
	v_fma_f32 v191, v128, v155, -v191
	v_mul_f32_e32 v155, v135, v155
	v_add_f32_e32 v156, v156, v191
	v_fmac_f32_e32 v155, v128, v154
	v_add_f32_e32 v154, v194, v155
	v_cvt_pk_bf16_f32 v155, v156, s0
	ds_write_b16 v166, v155
	v_cvt_pk_bf16_f32 v155, v154, s0
	ds_write_b16 v166, v155 offset:128
	v_mul_f32_e32 v155, v135, v154
	v_fma_f32 v155, v128, v156, -v155
	v_mul_f32_e32 v156, v135, v156
	v_add_f32_e32 v155, v157, v155
	v_fmac_f32_e32 v156, v128, v154
	v_add_f32_e32 v154, v195, v156
	v_cvt_pk_bf16_f32 v156, v155, s0
	ds_write_b16 v165, v156 offset:3264
	v_cvt_pk_bf16_f32 v156, v154, s0
	ds_write_b16 v165, v156 offset:3392
	v_mul_f32_e32 v156, v135, v154
	v_fma_f32 v156, v128, v155, -v156
	v_mul_f32_e32 v155, v135, v155
	v_add_f32_e32 v156, v196, v156
	v_fmac_f32_e32 v155, v128, v154
	v_add_f32_e32 v154, v200, v155
	v_cvt_pk_bf16_f32 v155, v156, s0
	ds_write_b16 v167, v155
	v_cvt_pk_bf16_f32 v155, v154, s0
	ds_write_b16 v167, v155 offset:128
	v_mul_f32_e32 v155, v135, v154
	v_fma_f32 v155, v128, v156, -v155
	v_mul_f32_e32 v156, v135, v156
	v_add_f32_e32 v155, v197, v155
	v_fmac_f32_e32 v156, v128, v154
	v_add_f32_e32 v154, v201, v156
	v_cvt_pk_bf16_f32 v156, v155, s0
	ds_write_b16 v165, v156 offset:5440
	v_cvt_pk_bf16_f32 v156, v154, s0
	ds_write_b16 v165, v156 offset:5568
	v_mul_f32_e32 v156, v135, v154
	v_fma_f32 v156, v128, v155, -v156
	v_mul_f32_e32 v155, v135, v155
	v_add_f32_e32 v156, v198, v156
	v_fmac_f32_e32 v155, v128, v154
	v_add_f32_e32 v154, v202, v155
	v_cvt_pk_bf16_f32 v155, v156, s0
	ds_write_b16 v168, v155
	v_cvt_pk_bf16_f32 v155, v154, s0
	ds_write_b16 v168, v155 offset:128
	v_mul_f32_e32 v155, v135, v154
	v_fma_f32 v155, v128, v156, -v155
	v_mul_f32_e32 v156, v135, v156
	v_add_f32_e32 v155, v199, v155
	v_fmac_f32_e32 v156, v128, v154
	v_add_f32_e32 v154, v203, v156
	v_cvt_pk_bf16_f32 v155, v155, s0
	ds_write_b16 v165, v155 offset:7616
	v_cvt_pk_bf16_f32 v154, v154, s0
	v_add_f32_e32 v155, v169, v104
	ds_write_b16 v165, v154 offset:7744
	v_add_f32_e32 v154, v170, v92
	v_mul_f32_e32 v156, v129, v155
	v_mul_f32_e32 v155, v120, v155
	v_fmac_f32_e32 v155, v129, v154
	v_fma_f32 v156, v120, v154, -v156
	v_add_f32_e32 v154, v105, v155
	v_add_f32_e32 v156, v93, v156
	v_mul_f32_e32 v155, v129, v154
	v_fma_f32 v155, v120, v156, -v155
	v_mul_f32_e32 v156, v129, v156
	v_fmac_f32_e32 v156, v120, v154
	v_add_f32_e32 v154, v106, v156
	v_add_f32_e32 v155, v94, v155
	v_mul_f32_e32 v156, v129, v154
	v_fma_f32 v156, v120, v155, -v156
	v_mul_f32_e32 v155, v129, v155
	v_fmac_f32_e32 v155, v120, v154
	v_add_f32_e32 v154, v107, v155
	v_add_f32_e32 v156, v95, v156
	v_mul_f32_e32 v155, v129, v154
	v_fma_f32 v155, v120, v156, -v155
	v_mul_f32_e32 v156, v129, v156
	v_fmac_f32_e32 v156, v120, v154
	v_add_f32_e32 v154, v100, v156
	v_add_f32_e32 v155, v96, v155
	v_mul_f32_e32 v156, v129, v154
	v_fma_f32 v156, v120, v155, -v156
	v_mul_f32_e32 v155, v129, v155
	v_fmac_f32_e32 v155, v120, v154
	v_add_f32_e32 v154, v101, v155
	v_add_f32_e32 v156, v97, v156
	v_mul_f32_e32 v155, v129, v154
	v_fma_f32 v155, v120, v156, -v155
	v_mul_f32_e32 v156, v129, v156
	v_fmac_f32_e32 v156, v120, v154
	v_add_f32_e32 v154, v102, v156
	v_add_f32_e32 v155, v98, v155
	v_mul_f32_e32 v156, v129, v154
	v_fma_f32 v156, v120, v155, -v156
	v_mul_f32_e32 v155, v129, v155
	v_fmac_f32_e32 v155, v120, v154
	v_add_f32_e32 v191, v99, v156
	v_add_f32_e32 v154, v103, v155
	ds_bpermute_b32 v157, v161, v191
	ds_bpermute_b32 v156, v161, v154
	v_mul_f32_e32 v155, v138, v122
	v_mul_f32_e32 v192, v138, v123
	v_fma_f32 v193, v136, v123, -v155
	v_fmac_f32_e32 v192, v136, v122
	ds_bpermute_b32 v195, v162, v191
	ds_bpermute_b32 v194, v162, v154
	s_waitcnt lgkmcnt(2)
	v_pk_add_f32 v[156:157], v[192:193], v[156:157]
	ds_bpermute_b32 v197, v163, v191
	ds_bpermute_b32 v155, v164, v191
	v_cndmask_b32_e32 v191, v123, v157, vcc
	v_cndmask_b32_e32 v198, v122, v156, vcc
	v_pk_mul_f32 v[122:123], v[138:139], v[156:157]
	ds_bpermute_b32 v196, v163, v154
	v_pk_fma_f32 v[192:193], v[136:137], v[156:157], v[122:123] op_sel:[0,0,1] op_sel_hi:[1,1,0]
	v_pk_fma_f32 v[122:123], v[136:137], v[156:157], v[122:123] op_sel:[0,0,1] op_sel_hi:[1,1,0] neg_lo:[0,0,1] neg_hi:[0,0,1]
	v_mfma_f32_16x16x32_bf16 v[76:79], v[44:47], v[28:31], 0
	v_mov_b32_e32 v193, v123
	s_waitcnt lgkmcnt(3)
	v_pk_add_f32 v[122:123], v[192:193], v[194:195]
	ds_bpermute_b32 v154, v164, v154
	v_pk_mul_f32 v[156:157], v[138:139], v[122:123]
	v_cndmask_b32_e64 v191, v191, v123, s[42:43]
	v_cndmask_b32_e64 v194, v198, v122, s[42:43]
	v_pk_fma_f32 v[192:193], v[136:137], v[122:123], v[156:157] op_sel:[0,0,1] op_sel_hi:[1,1,0]
	v_pk_fma_f32 v[122:123], v[136:137], v[122:123], v[156:157] op_sel:[0,0,1] op_sel_hi:[1,1,0] neg_lo:[0,0,1] neg_hi:[0,0,1]
	v_mfma_f32_16x16x32_bf16 v[48:51], v[44:47], v[4:7], 0
	v_mov_b32_e32 v193, v123
	s_waitcnt lgkmcnt(1)
	v_pk_add_f32 v[156:157], v[192:193], v[196:197]
	v_mov_b32_e32 v207, v111
	v_pk_mul_f32 v[192:193], v[138:139], v[156:157]
	v_cndmask_b32_e64 v194, v194, v156, s[44:45]
	v_pk_fma_f32 v[122:123], v[136:137], v[156:157], v[192:193] op_sel:[0,0,1] op_sel_hi:[1,1,0]
	v_cndmask_b32_e64 v191, v191, v157, s[44:45]
	v_mul_f32_e32 v123, v129, v194
	v_fma_f32 v123, v120, v191, -v123
	v_add_f32_e32 v92, v92, v123
	v_mul_f32_e32 v123, v129, v191
	v_fmac_f32_e32 v123, v120, v194
	v_add_f32_e32 v104, v104, v123
	v_cvt_pk_bf16_f32 v123, v92, s0
	ds_write_b16 v165, v123 offset:32
	v_cvt_pk_bf16_f32 v123, v104, s0
	ds_write_b16 v165, v123 offset:160
	v_mul_f32_e32 v123, v129, v104
	v_fma_f32 v123, v120, v92, -v123
	v_mul_f32_e32 v92, v129, v92
	v_add_f32_e32 v93, v93, v123
	v_fmac_f32_e32 v92, v120, v104
	v_add_f32_e32 v92, v105, v92
	v_cvt_pk_bf16_f32 v104, v93, s0
	ds_write_b16 v165, v104 offset:1120
	v_cvt_pk_bf16_f32 v104, v92, s0
	ds_write_b16 v165, v104 offset:1248
	v_mul_f32_e32 v104, v129, v92
	v_fma_f32 v104, v120, v93, -v104
	v_mul_f32_e32 v93, v129, v93
	v_add_f32_e32 v94, v94, v104
	v_fmac_f32_e32 v93, v120, v92
	v_add_f32_e32 v92, v106, v93
	v_cvt_pk_bf16_f32 v93, v94, s0
	ds_write_b16 v166, v93 offset:32
	v_cvt_pk_bf16_f32 v93, v92, s0
	ds_write_b16 v166, v93 offset:160
	v_mul_f32_e32 v93, v129, v92
	v_fma_f32 v93, v120, v94, -v93
	v_mul_f32_e32 v94, v129, v94
	v_add_f32_e32 v93, v95, v93
	v_fmac_f32_e32 v94, v120, v92
	v_add_f32_e32 v92, v107, v94
	v_cvt_pk_bf16_f32 v94, v93, s0
	ds_write_b16 v165, v94 offset:3296
	v_cvt_pk_bf16_f32 v94, v92, s0
	ds_write_b16 v165, v94 offset:3424
	v_mul_f32_e32 v94, v129, v92
	v_fma_f32 v94, v120, v93, -v94
	v_mul_f32_e32 v93, v129, v93
	v_add_f32_e32 v94, v96, v94
	v_fmac_f32_e32 v93, v120, v92
	v_add_f32_e32 v92, v100, v93
	v_cvt_pk_bf16_f32 v93, v94, s0
	ds_write_b16 v167, v93 offset:32
	v_cvt_pk_bf16_f32 v93, v92, s0
	ds_write_b16 v167, v93 offset:160
	v_mul_f32_e32 v93, v129, v92
	v_fma_f32 v93, v120, v94, -v93
	v_mul_f32_e32 v94, v129, v94
	v_add_f32_e32 v93, v97, v93
	v_fmac_f32_e32 v94, v120, v92
	v_add_f32_e32 v92, v101, v94
	v_cvt_pk_bf16_f32 v94, v93, s0
	ds_write_b16 v165, v94 offset:5472
	v_cvt_pk_bf16_f32 v94, v92, s0
	ds_write_b16 v165, v94 offset:5600
	v_mul_f32_e32 v94, v129, v92
	v_fma_f32 v94, v120, v93, -v94
	v_mul_f32_e32 v93, v129, v93
	v_add_f32_e32 v94, v98, v94
	v_fmac_f32_e32 v93, v120, v92
	v_add_f32_e32 v92, v102, v93
	v_cvt_pk_bf16_f32 v93, v94, s0
	ds_write_b16 v168, v93 offset:32
	v_cvt_pk_bf16_f32 v93, v92, s0
	ds_write_b16 v168, v93 offset:160
	v_mul_f32_e32 v93, v129, v92
	v_fma_f32 v93, v120, v94, -v93
	v_mul_f32_e32 v94, v129, v94
	v_add_f32_e32 v93, v99, v93
	v_fmac_f32_e32 v94, v120, v92
	v_add_f32_e32 v92, v103, v94
	v_cvt_pk_bf16_f32 v93, v93, s0
	ds_write_b16 v165, v93 offset:7648
	v_cvt_pk_bf16_f32 v92, v92, s0
	v_add_f32_e32 v93, v171, v88
	ds_write_b16 v165, v92 offset:7776
	v_add_f32_e32 v92, v172, v84
	v_mul_f32_e32 v94, v121, v93
	v_mul_f32_e32 v93, v114, v93
	v_fmac_f32_e32 v93, v121, v92
	v_fma_f32 v94, v114, v92, -v94
	v_add_f32_e32 v92, v89, v93
	v_add_f32_e32 v94, v85, v94
	v_mul_f32_e32 v93, v121, v92
	v_fma_f32 v93, v114, v94, -v93
	v_mul_f32_e32 v94, v121, v94
	v_fmac_f32_e32 v94, v114, v92
	v_add_f32_e32 v92, v90, v94
	v_add_f32_e32 v93, v86, v93
	v_mul_f32_e32 v94, v121, v92
	v_fma_f32 v94, v114, v93, -v94
	v_mul_f32_e32 v93, v121, v93
	v_fmac_f32_e32 v93, v114, v92
	v_add_f32_e32 v92, v91, v93
	v_add_f32_e32 v94, v87, v94
	v_mul_f32_e32 v93, v121, v92
	v_fma_f32 v93, v114, v94, -v93
	v_mul_f32_e32 v94, v121, v94
	v_fmac_f32_e32 v94, v114, v92
	v_add_f32_e32 v92, v80, v94
	v_add_f32_e32 v93, v76, v93
	v_mul_f32_e32 v94, v121, v92
	v_fma_f32 v94, v114, v93, -v94
	v_mul_f32_e32 v93, v121, v93
	v_fmac_f32_e32 v93, v114, v92
	v_add_f32_e32 v92, v81, v93
	v_add_f32_e32 v94, v77, v94
	v_mul_f32_e32 v93, v121, v92
	v_fma_f32 v93, v114, v94, -v93
	v_mul_f32_e32 v94, v121, v94
	v_fmac_f32_e32 v94, v114, v92
	v_add_f32_e32 v92, v82, v94
	v_add_f32_e32 v93, v78, v93
	v_mul_f32_e32 v94, v121, v92
	v_fma_f32 v94, v114, v93, -v94
	v_mul_f32_e32 v93, v121, v93
	v_fmac_f32_e32 v93, v114, v92
	v_add_f32_e32 v102, v79, v94
	v_add_f32_e32 v103, v83, v93
	ds_bpermute_b32 v93, v161, v102
	ds_bpermute_b32 v92, v161, v103
	v_mul_f32_e32 v94, v132, v118
	v_fma_f32 v95, v130, v119, -v94
	v_mul_f32_e32 v94, v132, v119
	v_fmac_f32_e32 v94, v130, v118
	ds_bpermute_b32 v97, v162, v102
	ds_bpermute_b32 v96, v162, v103
	s_waitcnt lgkmcnt(2)
	v_pk_add_f32 v[92:93], v[94:95], v[92:93]
	ds_bpermute_b32 v99, v163, v102
	v_pk_mul_f32 v[94:95], v[132:133], v[92:93]
	v_cndmask_b32_e32 v104, v119, v93, vcc
	v_cndmask_b32_e32 v105, v118, v92, vcc
	v_pk_fma_f32 v[100:101], v[130:131], v[92:93], v[94:95] op_sel:[0,0,1] op_sel_hi:[1,1,0]
	v_pk_fma_f32 v[92:93], v[130:131], v[92:93], v[94:95] op_sel:[0,0,1] op_sel_hi:[1,1,0] neg_lo:[0,0,1] neg_hi:[0,0,1]
	ds_bpermute_b32 v98, v163, v103
	v_mov_b32_e32 v101, v93
	s_waitcnt lgkmcnt(2)
	v_pk_add_f32 v[92:93], v[100:101], v[96:97]
	v_mfma_f32_16x16x32_bf16 v[44:47], v[44:47], v[8:11], 0
	v_mul_f32_e64 v94, v132, v92
	v_mul_f32_e64 v95, v133, v93
	v_cndmask_b32_e64 v100, v104, v93, s[42:43]
	v_cndmask_b32_e64 v101, v105, v92, s[42:43]
	v_pk_fma_f32 v[96:97], v[130:131], v[92:93], v[94:95] op_sel:[0,0,1] op_sel_hi:[1,1,0]
	v_pk_fma_f32 v[92:93], v[130:131], v[92:93], v[94:95] op_sel:[0,0,1] op_sel_hi:[1,1,0] neg_lo:[0,0,1] neg_hi:[0,0,1]
	v_pk_fma_f32 v[156:157], v[136:137], v[156:157], v[192:193] op_sel:[0,0,1] op_sel_hi:[1,1,0] neg_lo:[0,0,1] neg_hi:[0,0,1]
	v_mov_b32_e32 v97, v93
	s_waitcnt lgkmcnt(0)
	v_pk_add_f32 v[92:93], v[96:97], v[98:99]
	v_mov_b32_e32 v123, v157
	v_cndmask_b32_e64 v95, v101, v92, s[44:45]
	v_cndmask_b32_e64 v94, v100, v93, s[44:45]
	v_mul_f32_e32 v96, v121, v95
	v_fma_f32 v96, v114, v94, -v96
	v_mul_f32_e32 v94, v121, v94
	v_add_f32_e32 v84, v84, v96
	v_fmac_f32_e32 v94, v114, v95
	v_add_f32_e32 v88, v88, v94
	v_cvt_pk_bf16_f32 v94, v84, s0
	ds_write_b16 v165, v94 offset:64
	v_cvt_pk_bf16_f32 v94, v88, s0
	ds_write_b16 v165, v94 offset:192
	v_mul_f32_e32 v94, v121, v88
	v_fma_f32 v94, v114, v84, -v94
	v_mul_f32_e32 v84, v121, v84
	v_add_f32_e32 v85, v85, v94
	v_fmac_f32_e32 v84, v114, v88
	v_add_f32_e32 v84, v89, v84
	v_cvt_pk_bf16_f32 v88, v85, s0
	ds_write_b16 v165, v88 offset:1152
	v_cvt_pk_bf16_f32 v88, v84, s0
	ds_write_b16 v165, v88 offset:1280
	v_mul_f32_e32 v88, v121, v84
	v_fma_f32 v88, v114, v85, -v88
	v_mul_f32_e32 v85, v121, v85
	v_add_f32_e32 v86, v86, v88
	v_fmac_f32_e32 v85, v114, v84
	v_add_f32_e32 v84, v90, v85
	v_cvt_pk_bf16_f32 v85, v86, s0
	ds_write_b16 v166, v85 offset:64
	v_cvt_pk_bf16_f32 v85, v84, s0
	ds_write_b16 v166, v85 offset:192
	v_mul_f32_e32 v85, v121, v84
	v_fma_f32 v85, v114, v86, -v85
	v_mul_f32_e32 v86, v121, v86
	v_add_f32_e32 v85, v87, v85
	v_fmac_f32_e32 v86, v114, v84
	v_add_f32_e32 v84, v91, v86
	v_cvt_pk_bf16_f32 v86, v85, s0
	ds_write_b16 v165, v86 offset:3328
	v_cvt_pk_bf16_f32 v86, v84, s0
	ds_write_b16 v165, v86 offset:3456
	v_mul_f32_e32 v86, v121, v84
	v_fma_f32 v86, v114, v85, -v86
	v_mul_f32_e32 v85, v121, v85
	v_add_f32_e32 v76, v76, v86
	v_fmac_f32_e32 v85, v114, v84
	v_add_f32_e32 v80, v80, v85
	v_cvt_pk_bf16_f32 v84, v76, s0
	ds_write_b16 v167, v84 offset:64
	v_cvt_pk_bf16_f32 v84, v80, s0
	ds_write_b16 v167, v84 offset:192
	v_mul_f32_e32 v84, v121, v80
	v_fma_f32 v84, v114, v76, -v84
	v_mul_f32_e32 v76, v121, v76
	v_add_f32_e32 v77, v77, v84
	v_fmac_f32_e32 v76, v114, v80
	v_add_f32_e32 v76, v81, v76
	v_cvt_pk_bf16_f32 v80, v77, s0
	ds_write_b16 v165, v80 offset:5504
	v_cvt_pk_bf16_f32 v80, v76, s0
	ds_write_b16 v165, v80 offset:5632
	v_mul_f32_e32 v80, v121, v76
	v_fma_f32 v80, v114, v77, -v80
	v_mul_f32_e32 v77, v121, v77
	v_add_f32_e32 v78, v78, v80
	v_fmac_f32_e32 v77, v114, v76
	v_add_f32_e32 v76, v82, v77
	v_cvt_pk_bf16_f32 v77, v78, s0
	ds_write_b16 v168, v77 offset:64
	v_cvt_pk_bf16_f32 v77, v76, s0
	ds_write_b16 v168, v77 offset:192
	v_mul_f32_e32 v77, v121, v76
	v_fma_f32 v77, v114, v78, -v77
	v_mul_f32_e32 v78, v121, v78
	v_add_f32_e32 v77, v79, v77
	v_fmac_f32_e32 v78, v114, v76
	v_add_f32_e32 v76, v83, v78
	v_cvt_pk_bf16_f32 v77, v77, s0
	ds_write_b16 v165, v77 offset:7680
	v_cvt_pk_bf16_f32 v76, v76, s0
	v_add_f32_e32 v77, v173, v72
	ds_write_b16 v165, v76 offset:7808
	v_add_f32_e32 v76, v174, v68
	v_mul_f32_e32 v78, v115, v77
	v_mul_f32_e32 v77, v159, v77
	v_fmac_f32_e32 v77, v115, v76
	v_fma_f32 v78, v159, v76, -v78
	v_add_f32_e32 v76, v73, v77
	v_add_f32_e32 v78, v69, v78
	v_mul_f32_e32 v77, v115, v76
	v_fma_f32 v77, v159, v78, -v77
	v_mul_f32_e32 v78, v115, v78
	v_fmac_f32_e32 v78, v159, v76
	v_add_f32_e32 v76, v74, v78
	v_add_f32_e32 v77, v70, v77
	v_mul_f32_e32 v78, v115, v76
	v_fma_f32 v78, v159, v77, -v78
	v_mul_f32_e32 v77, v115, v77
	v_fmac_f32_e32 v77, v159, v76
	v_add_f32_e32 v76, v75, v77
	v_add_f32_e32 v78, v71, v78
	v_mul_f32_e32 v77, v115, v76
	v_fma_f32 v77, v159, v78, -v77
	v_mul_f32_e32 v78, v115, v78
	v_fmac_f32_e32 v78, v159, v76
	v_add_f32_e32 v76, v44, v78
	v_add_f32_e32 v77, v48, v77
	v_mul_f32_e32 v78, v115, v76
	v_fma_f32 v78, v159, v77, -v78
	v_mul_f32_e32 v77, v115, v77
	v_fmac_f32_e32 v77, v159, v76
	v_add_f32_e32 v76, v45, v77
	v_add_f32_e32 v78, v49, v78
	v_mul_f32_e32 v77, v115, v76
	v_fma_f32 v77, v159, v78, -v77
	v_mul_f32_e32 v78, v115, v78
	v_fmac_f32_e32 v78, v159, v76
	v_add_f32_e32 v76, v46, v78
	v_add_f32_e32 v77, v50, v77
	v_mul_f32_e32 v78, v115, v76
	v_fma_f32 v78, v159, v77, -v78
	v_mul_f32_e32 v77, v115, v77
	v_fmac_f32_e32 v77, v159, v76
	v_add_f32_e32 v86, v51, v78
	v_add_f32_e32 v87, v47, v77
	ds_bpermute_b32 v77, v161, v86
	ds_bpermute_b32 v76, v161, v87
	v_mul_f32_e32 v78, v126, v116
	v_fma_f32 v79, v124, v117, -v78
	v_mul_f32_e32 v78, v126, v117
	v_fmac_f32_e32 v78, v124, v116
	ds_bpermute_b32 v81, v162, v86
	ds_bpermute_b32 v80, v162, v87
	s_waitcnt lgkmcnt(2)
	v_pk_add_f32 v[76:77], v[78:79], v[76:77]
	ds_bpermute_b32 v83, v163, v86
	v_pk_mul_f32 v[78:79], v[126:127], v[76:77]
	v_cndmask_b32_e32 v88, v117, v77, vcc
	v_cndmask_b32_e32 v89, v116, v76, vcc
	v_pk_fma_f32 v[84:85], v[124:125], v[76:77], v[78:79] op_sel:[0,0,1] op_sel_hi:[1,1,0]
	v_pk_fma_f32 v[76:77], v[124:125], v[76:77], v[78:79] op_sel:[0,0,1] op_sel_hi:[1,1,0] neg_lo:[0,0,1] neg_hi:[0,0,1]
	ds_bpermute_b32 v82, v163, v87
	v_mov_b32_e32 v85, v77
	s_waitcnt lgkmcnt(2)
	v_pk_add_f32 v[76:77], v[84:85], v[80:81]
	v_pk_add_f32 v[110:111], v[206:207], v[212:213]
	v_pk_mul_f32 v[78:79], v[126:127], v[76:77]
	v_cndmask_b32_e64 v84, v88, v77, s[42:43]
	v_cndmask_b32_e64 v85, v89, v76, s[42:43]
	v_pk_fma_f32 v[80:81], v[124:125], v[76:77], v[78:79] op_sel:[0,0,1] op_sel_hi:[1,1,0]
	v_pk_fma_f32 v[76:77], v[124:125], v[76:77], v[78:79] op_sel:[0,0,1] op_sel_hi:[1,1,0] neg_lo:[0,0,1] neg_hi:[0,0,1]
	v_pk_add_f32 v[122:123], v[122:123], v[154:155]
	v_mov_b32_e32 v81, v77
	s_waitcnt lgkmcnt(0)
	v_pk_add_f32 v[76:77], v[80:81], v[82:83]
	s_nop 0
	v_cndmask_b32_e64 v79, v85, v76, s[44:45]
	v_cndmask_b32_e64 v78, v84, v77, s[44:45]
	v_mul_f32_e32 v80, v115, v79
	v_fma_f32 v80, v159, v78, -v80
	v_mul_f32_e32 v78, v115, v78
	v_add_f32_e32 v68, v68, v80
	v_fmac_f32_e32 v78, v159, v79
	v_add_f32_e32 v72, v72, v78
	v_cvt_pk_bf16_f32 v78, v68, s0
	ds_write_b16 v165, v78 offset:96
	v_cvt_pk_bf16_f32 v78, v72, s0
	ds_write_b16 v165, v78 offset:224
	v_mul_f32_e32 v78, v115, v72
	v_fma_f32 v78, v159, v68, -v78
	v_mul_f32_e32 v68, v115, v68
	v_add_f32_e32 v69, v69, v78
	v_fmac_f32_e32 v68, v159, v72
	v_add_f32_e32 v68, v73, v68
	v_cvt_pk_bf16_f32 v72, v69, s0
	ds_write_b16 v165, v72 offset:1184
	v_cvt_pk_bf16_f32 v72, v68, s0
	ds_write_b16 v165, v72 offset:1312
	v_mul_f32_e32 v72, v115, v68
	v_fma_f32 v72, v159, v69, -v72
	v_mul_f32_e32 v69, v115, v69
	v_add_f32_e32 v70, v70, v72
	v_fmac_f32_e32 v69, v159, v68
	v_add_f32_e32 v68, v74, v69
	v_cvt_pk_bf16_f32 v69, v70, s0
	ds_write_b16 v166, v69 offset:96
	v_cvt_pk_bf16_f32 v69, v68, s0
	ds_write_b16 v166, v69 offset:224
	v_mul_f32_e32 v69, v115, v68
	v_fma_f32 v69, v159, v70, -v69
	v_mul_f32_e32 v70, v115, v70
	v_add_f32_e32 v69, v71, v69
	v_fmac_f32_e32 v70, v159, v68
	v_add_f32_e32 v68, v75, v70
	v_cvt_pk_bf16_f32 v70, v69, s0
	ds_write_b16 v165, v70 offset:3360
	v_cvt_pk_bf16_f32 v70, v68, s0
	ds_write_b16 v165, v70 offset:3488
	v_mul_f32_e32 v70, v115, v68
	v_fma_f32 v70, v159, v69, -v70
	v_mul_f32_e32 v69, v115, v69
	v_add_f32_e32 v48, v48, v70
	v_fmac_f32_e32 v69, v159, v68
	v_add_f32_e32 v44, v44, v69
	v_cvt_pk_bf16_f32 v68, v48, s0
	ds_write_b16 v167, v68 offset:96
	v_cvt_pk_bf16_f32 v68, v44, s0
	ds_write_b16 v167, v68 offset:224
	v_mul_f32_e32 v68, v115, v44
	v_fma_f32 v68, v159, v48, -v68
	v_mul_f32_e32 v48, v115, v48
	v_add_f32_e32 v49, v49, v68
	v_fmac_f32_e32 v48, v159, v44
	v_add_f32_e32 v44, v45, v48
	v_cvt_pk_bf16_f32 v45, v49, s0
	ds_write_b16 v165, v45 offset:5536
	v_cvt_pk_bf16_f32 v45, v44, s0
	ds_write_b16 v165, v45 offset:5664
	v_mul_f32_e32 v45, v115, v44
	v_fma_f32 v45, v159, v49, -v45
	v_mul_f32_e32 v48, v115, v49
	v_add_f32_e32 v45, v50, v45
	v_fmac_f32_e32 v48, v159, v44
	v_add_f32_e32 v44, v46, v48
	v_cvt_pk_bf16_f32 v46, v45, s0
	ds_write_b16 v168, v46 offset:96
	v_cvt_pk_bf16_f32 v46, v44, s0
	ds_write_b16 v168, v46 offset:224
	v_mul_f32_e32 v46, v115, v44
	v_fma_f32 v46, v159, v45, -v46
	v_mul_f32_e32 v45, v115, v45
	v_fmac_f32_e32 v45, v159, v44
	v_add_f32_e32 v46, v51, v46
	v_add_f32_e32 v44, v47, v45
	v_cvt_pk_bf16_f32 v45, v46, s0
	v_cvt_pk_bf16_f32 v44, v44, s0
	ds_write_b16 v165, v45 offset:7712
	ds_write_b16 v165, v44 offset:7840
	s_waitcnt lgkmcnt(0)
	ds_read_b128 v[44:47], v190
	ds_read_b128 v[48:51], v190 offset:64
	s_waitcnt lgkmcnt(1)
	v_mfma_f32_16x16x32_bf16 v[44:47], v[12:15], v[44:47], 0
	ds_read_b128 v[68:71], v190 offset:128
	ds_bpermute_b32 v73, v164, v102
	ds_bpermute_b32 v72, v164, v103
	s_waitcnt lgkmcnt(3)
	v_mfma_f32_16x16x32_bf16 v[44:47], v[16:19], v[48:51], v[44:47]
	ds_read_b128 v[48:51], v190 offset:192
	v_pk_mul_f32 v[74:75], v[132:133], v[92:93]
	v_pk_mul_f32 v[80:81], v[126:127], v[76:77]
	s_waitcnt lgkmcnt(3)
	v_mfma_f32_16x16x32_bf16 v[44:47], v[20:23], v[68:71], v[44:47]
	ds_read_b128 v[68:71], v190 offset:544
	v_pk_fma_f32 v[78:79], v[130:131], v[92:93], v[74:75] op_sel:[0,0,1] op_sel_hi:[1,1,0]
	v_pk_fma_f32 v[74:75], v[130:131], v[92:93], v[74:75] op_sel:[0,0,1] op_sel_hi:[1,1,0] neg_lo:[0,0,1] neg_hi:[0,0,1]
	s_waitcnt lgkmcnt(1)
	v_mfma_f32_16x16x32_bf16 v[44:47], v[24:27], v[48:51], v[44:47]
	ds_read_b128 v[48:51], v190 offset:608
	v_mov_b32_e32 v79, v75
	v_pk_add_f32 v[118:119], v[78:79], v[72:73]
	s_waitcnt lgkmcnt(1)
	v_mfma_f32_16x16x32_bf16 v[68:71], v[12:15], v[68:71], 0
	ds_read_b128 v[72:75], v190 offset:672
	v_pk_fma_f32 v[82:83], v[124:125], v[76:77], v[80:81] op_sel:[0,0,1] op_sel_hi:[1,1,0]
	ds_bpermute_b32 v79, v164, v86
	s_waitcnt lgkmcnt(2)
	v_mfma_f32_16x16x32_bf16 v[48:51], v[16:19], v[48:51], v[68:71]
	ds_bpermute_b32 v78, v164, v87
	s_nop 1
	v_pk_fma_f32 v[68:69], v[124:125], v[76:77], v[80:81] op_sel:[0,0,1] op_sel_hi:[1,1,0] neg_lo:[0,0,1] neg_hi:[0,0,1]
	s_nop 0
	v_mov_b32_e32 v83, v69
	ds_read_b128 v[68:71], v190 offset:736
	s_waitcnt lgkmcnt(3)
	v_mfma_f32_16x16x32_bf16 v[48:51], v[20:23], v[72:75], v[48:51]
	s_waitcnt vmcnt(1)
	v_lshlrev_b32_e32 v72, 16, v152
	v_and_b32_e32 v73, 0xffff0000, v152
	v_pk_fma_f32 v[72:73], v[0:1], v[72:73], v[44:45]
	v_lshlrev_b32_e32 v74, 16, v153
	v_mul_f32_e32 v44, 0x3d372713, v72
	v_mul_f32_e32 v44, v72, v44
	v_mul_f32_e32 v45, 0x3d372713, v73
	v_fma_f32 v44, v72, v44, v72
	v_mul_f32_e32 v45, v73, v45
	v_mul_f32_e32 v44, 0x3fcc422a, v44
	v_fma_f32 v45, v73, v45, v73
	v_mul_f32_e32 v44, 0xbfb8aa3b, v44
	v_mul_f32_e32 v45, 0x3fcc422a, v45
	v_exp_f32_e32 v44, v44
	v_mul_f32_e32 v45, 0xbfb8aa3b, v45
	v_exp_f32_e32 v45, v45
	v_and_b32_e32 v75, 0xffff0000, v153
	v_pk_fma_f32 v[74:75], v[2:3], v[74:75], v[46:47]
	v_add_f32_e32 v44, 1.0, v44
	v_rcp_f32_e32 v76, v44
	v_add_f32_e32 v44, 1.0, v45
	v_mul_f32_e32 v45, 0x3d372713, v74
	v_mul_f32_e32 v45, v74, v45
	v_mul_f32_e32 v46, 0x3d372713, v75
	v_fma_f32 v45, v74, v45, v74
	v_mul_f32_e32 v46, v75, v46
	v_mul_f32_e32 v45, 0x3fcc422a, v45
	v_fma_f32 v46, v75, v46, v75
	v_mul_f32_e32 v45, 0xbfb8aa3b, v45
	v_mul_f32_e32 v46, 0x3fcc422a, v46
	v_exp_f32_e32 v45, v45
	v_mul_f32_e32 v46, 0xbfb8aa3b, v46
	v_exp_f32_e32 v46, v46
	v_rcp_f32_e32 v77, v44
	v_add_f32_e32 v44, 1.0, v45
	v_rcp_f32_e32 v80, v44
	v_add_f32_e32 v44, 1.0, v46
	v_rcp_f32_e32 v81, v44
	s_waitcnt lgkmcnt(0)
	v_mfma_f32_16x16x32_bf16 v[44:47], v[24:27], v[68:71], v[48:51]
	s_waitcnt vmcnt(0)
	v_lshlrev_b32_e32 v68, 16, v150
	v_and_b32_e32 v69, 0xffff0000, v150
	v_lshlrev_b32_e32 v70, 16, v151
	v_pk_mul_f32 v[48:49], v[72:73], v[76:77]
	v_and_b32_e32 v71, 0xffff0000, v151
	s_nop 1
	v_pk_fma_f32 v[44:45], v[0:1], v[68:69], v[44:45]
	v_cvt_pk_bf16_f32 v48, v48, v49
	v_mul_f32_e32 v49, 0x3d372713, v44
	v_mul_f32_e32 v49, v44, v49
	v_mul_f32_e32 v68, 0x3d372713, v45
	v_fma_f32 v49, v44, v49, v44
	v_mul_f32_e32 v68, v45, v68
	v_mul_f32_e32 v49, 0x3fcc422a, v49
	v_fma_f32 v68, v45, v68, v45
	v_mul_f32_e32 v49, 0xbfb8aa3b, v49
	v_mul_f32_e32 v68, 0x3fcc422a, v68
	v_exp_f32_e32 v49, v49
	v_mul_f32_e32 v68, 0xbfb8aa3b, v68
	v_exp_f32_e32 v69, v68
	v_pk_fma_f32 v[46:47], v[2:3], v[70:71], v[46:47]
	v_add_f32_e32 v49, 1.0, v49
	v_rcp_f32_e32 v68, v49
	v_add_f32_e32 v49, 1.0, v69
	v_mul_f32_e32 v69, 0x3d372713, v46
	v_mul_f32_e32 v69, v46, v69
	v_fma_f32 v69, v46, v69, v46
	v_mul_f32_e32 v69, 0x3fcc422a, v69
	v_mul_f32_e32 v69, 0xbfb8aa3b, v69
	v_exp_f32_e32 v70, v69
	v_mul_f32_e32 v69, 0x3d372713, v47
	v_mul_f32_e32 v69, v47, v69
	v_fma_f32 v69, v47, v69, v47
	v_mul_f32_e32 v69, 0x3fcc422a, v69
	v_mul_f32_e32 v69, 0xbfb8aa3b, v69
	v_exp_f32_e32 v71, v69
	v_rcp_f32_e32 v69, v49
	v_add_f32_e32 v49, 1.0, v70
	v_rcp_f32_e32 v70, v49
	v_add_f32_e32 v49, 1.0, v71
	v_rcp_f32_e32 v71, v49
	v_pk_mul_f32 v[50:51], v[74:75], v[80:81]
	v_pk_mul_f32 v[44:45], v[44:45], v[68:69]
	v_cvt_pk_bf16_f32 v49, v50, v51
	v_pk_mul_f32 v[46:47], v[46:47], v[70:71]
	v_cvt_pk_bf16_f32 v44, v44, v45
	v_cvt_pk_bf16_f32 v45, v46, v47
	global_store_dwordx2 v[148:149], v[48:49], off
	global_store_dwordx2 v[146:147], v[44:45], off
	v_pk_add_f32 v[116:117], v[82:83], v[78:79]
	s_cbranch_scc0 .LBB0_856
	v_cmp_eq_u32_e32 vcc, 0, v158
	s_and_saveexec_b64 s[22:23], vcc
	s_cbranch_execz .LBB0_645
	s_ashr_i32 s89, s88, 31
	s_and_b64 s[40:41], exec, s[2:3]
	s_cselect_b32 s29, 15, 14
	s_mov_b32 s40, 0x6080000
	v_readlane_b32 s30, v250, 58
	s_cselect_b32 s40, s40, 0x62f8000
	s_lshl_b32 s29, s30, s29
	s_or_b32 s86, s29, s40
	s_lshl_b64 s[40:41], s[88:89], 13
	s_add_u32 s42, s26, s40
	s_addc_u32 s43, s27, s41
	s_lshl_b64 s[40:41], s[86:87], 2
	s_add_u32 s40, s42, s40
	s_addc_u32 s41, s43, s41
	s_and_b64 s[2:3], exec, s[2:3]
	s_mov_b32 s2, 0x6090000
	s_cselect_b32 s2, s2, 0x6300000
	s_or_b32 s86, s29, s2
	s_lshl_b64 s[2:3], s[86:87], 2
	s_add_u32 s2, s42, s2
	v_lshlrev_b64 v[0:1], 2, v[108:109]
	s_addc_u32 s3, s43, s3
	v_lshl_add_u64 v[2:3], s[40:41], 0, v[0:1]
	v_lshl_add_u64 v[0:1], s[2:3], 0, v[0:1]
	v_lshlrev_b32_e32 v176, 2, v176
	v_lshl_add_u64 v[2:3], v[2:3], 0, v[176:177]
	v_lshl_add_u64 v[0:1], v[0:1], 0, v[176:177]
	v_readlane_b32 s31, v250, 59
	global_store_dword v[2:3], v111, off
	global_store_dword v[0:1], v110, off
	global_store_dword v[2:3], v123, off offset:64
	global_store_dword v[0:1], v122, off offset:64
	global_store_dword v[2:3], v119, off offset:128
	global_store_dword v[0:1], v118, off offset:128
	global_store_dword v[2:3], v117, off offset:192
	global_store_dword v[0:1], v116, off offset:192
	s_branch .LBB0_645
